# HGRN pass A and C next-item prefetch loads use scalar row bases (saddr form) instead of per-load 64-bit VALU address math
# speedup vs baseline: 1.0387x; 1.0004x over previous
; DI void hgA_load(unsigned char* ws, int item, unsigned (&lf)[16], u32x4 (&ivw)[2]) {
;     const int tid = threadIdx.x, b = item >> 10, h = (item >> 6) & 15, c = item & 63, t0 = b * SEQ + c * 64, k = tid & 127, tq = tid >> 7;
;     const bf16_t* LOGF = (const bf16_t*)(ws + WS_LOGF);
; #pragma unroll
;     for (int i = 0; i < 16; ++i) lf[i] = LOGF[(size_t)(t0 + tq * 16 + i) * DM + h * 128 + k];
;     hg_iv_load((const bf16_t*)(ws + WS_IV), item, ivw);
; __global__ void __launch_bounds__(512, 2) fwd_kernel(Args a) {
;     ...
;             const int nx = it + G; unsigned lfb[16]; u32x4 ivb[2];
; #pragma unroll
;             for (int i = 0; i < 16; ++i) lfb[i] = 0u;
;             ivb[0] = iva[0]; ivb[1] = iva[1];
;             if (nx < 2048) hgA_load(ws, nx, lfb, ivb);
.LBB0_989:
	s_add_i32 s36, s37, s58
	s_cmpk_gt_i32 s36, 0x7ff
	s_cselect_b64 s[16:17], -1, 0
	s_and_b64 vcc, exec, s[16:17]
	v_mov_b32_e32 v59, 0
	v_mov_b32_e32 v60, 0
	v_mov_b32_e32 v61, 0
	v_mov_b32_e32 v62, 0
	v_mov_b32_e32 v63, 0
	v_mov_b32_e32 v64, 0
	v_mov_b32_e32 v65, 0
	v_mov_b32_e32 v66, 0
	v_mov_b32_e32 v67, 0
	v_mov_b32_e32 v68, 0
	v_mov_b32_e32 v69, 0
	v_mov_b32_e32 v70, 0
	v_mov_b32_e32 v71, 0
	v_mov_b32_e32 v72, 0
	v_mov_b32_e32 v73, 0
	v_mov_b32_e32 v74, 0
	s_bfe_u32 s18, s37, 0x40006
	v_lshlrev_b32_e32 v100, 2, v45
	v_lshl_or_b32 v100, s18, 9, v100
	global_load_dword v100, v100, s[24:25]
	s_cbranch_vccnz .LBB0_991
	s_and_b32 s10, s23, 0xfffff000
	s_and_b32 s18, s27, 0xfc0
	s_or_b32 s10, s10, s18
	v_readlane_b32 s18, v254, 3
	s_nop 0
	s_lshl_b32 s18, s18, 3
	s_and_b32 s18, s18, 48
	s_add_i32 s10, s10, s18
	s_lshl_b32 s40, s10, 12
	s_and_b32 s10, s29, 0x780
	s_lshl_b32 s10, s10, 1
	s_add_u32 s40, s40, s10
	s_add_u32 s40, s40, 0x8c80000
	s_add_u32 s40, s82, s40
	s_addc_u32 s41, s83, 0
	v_lshlrev_b32_e32 v24, 1, v45
	global_load_ushort v59, v24, s[40:41]
	s_add_u32 s40, s40, 0x1000
	s_addc_u32 s41, s41, 0
	global_load_ushort v60, v24, s[40:41]
	s_add_u32 s40, s40, 0x1000
	s_addc_u32 s41, s41, 0
	global_load_ushort v61, v24, s[40:41]
	s_add_u32 s40, s40, 0x1000
	s_addc_u32 s41, s41, 0
	global_load_ushort v62, v24, s[40:41]
	s_add_u32 s40, s40, 0x1000
	s_addc_u32 s41, s41, 0
	global_load_ushort v63, v24, s[40:41]
	s_add_u32 s40, s40, 0x1000
	s_addc_u32 s41, s41, 0
	global_load_ushort v64, v24, s[40:41]
	s_add_u32 s40, s40, 0x1000
	s_addc_u32 s41, s41, 0
	global_load_ushort v65, v24, s[40:41]
	s_add_u32 s40, s40, 0x1000
	s_addc_u32 s41, s41, 0
	global_load_ushort v66, v24, s[40:41]
	s_add_u32 s40, s40, 0x1000
	s_addc_u32 s41, s41, 0
	global_load_ushort v67, v24, s[40:41]
	s_add_u32 s40, s40, 0x1000
	s_addc_u32 s41, s41, 0
	global_load_ushort v68, v24, s[40:41]
	s_add_u32 s40, s40, 0x1000
	s_addc_u32 s41, s41, 0
	global_load_ushort v69, v24, s[40:41]
	s_add_u32 s40, s40, 0x1000
	s_addc_u32 s41, s41, 0
	global_load_ushort v70, v24, s[40:41]
	s_add_u32 s40, s40, 0x1000
	s_addc_u32 s41, s41, 0
	global_load_ushort v71, v24, s[40:41]
	s_add_u32 s40, s40, 0x1000
	s_addc_u32 s41, s41, 0
	global_load_ushort v72, v24, s[40:41]
	s_add_u32 s40, s40, 0x1000
	s_addc_u32 s41, s41, 0
	global_load_ushort v73, v24, s[40:41]
	s_add_u32 s40, s40, 0x1000
	s_addc_u32 s41, s41, 0
	global_load_ushort v74, v24, s[40:41]
	v_add_co_u32_e32 v24, vcc, 0xffffe000, v48
	s_nop 1
	v_addc_co_u32_e32 v25, vcc, -1, v49, vcc
	global_load_dwordx4 v[36:39], v[24:25], off
	global_load_dwordx4 v[32:35], v[48:49], off

; DI bf16_t* ds_item_ptr(unsigned char* ws, unsigned char* ob, int b, int h, int c) { return (bf16_t*)(b == 0 ? ws + WS_DS0 : ob) + ((size_t)(h * 64 + c)) * 16384; }
; DI void hgC_load(unsigned char* ws, int item, unsigned (&lf)[16], unsigned (&qv)[16], u32x4 (&ivw)[2]) {
;     const int tid = threadIdx.x, b = item >> 10, h = (item >> 6) & 15, c = item & 63, t0 = b * SEQ + c * 64, kp = tid & 63, tq = tid >> 6;
;     const bf16_t* LOGF = (const bf16_t*)(ws + WS_LOGF);
;     const bf16_t* Q2 = (const bf16_t*)(ws + WS_Q2);
; #pragma unroll
;     for (int i = 0; i < 8; ++i) { const size_t o = (size_t)(t0 + tq * 8 + i) * DM + h * 128 + 2 * kp; lf[i] = *(const unsigned*)(LOGF + o); qv[i] = *(const unsigned*)(Q2 + o); }
;     hg_iv_load((const bf16_t*)(ws + WS_IV), item, ivw);
; DI void hgC_item(LAS unsigned char* lds, unsigned char* ws, unsigned char* ob, int item, const float* ng, int dummy, const unsigned (&lfr)[16], const unsigned (&qvr)[16], const u32x4 (&ivw)[2], const float* lbp) {
;     ...
;     u32x4 sreg[4], gz[2];
;     { const bf16_t* Sg = ds_item_ptr(ws, ob, b, h, c);
; #pragma unroll
;       for (int j = 0; j < 4; ++j) sreg[j] = *(const u32x4*)(Sg + (size_t)(tid + 512 * j) * 8);
; #pragma unroll
;       for (int j = 0; j < 2; ++j) { const int id = tid + 512 * j; gz[j] = *(const u32x4*)(G2 + (size_t)(t0 + (id >> 4)) * DM + h * 128 + (id & 15) * 8); } }
;     float kk0[8], kk1[8], q0v[8], q1v[8], cs0[8], cs1[8];
;     {
;         const f32x2 lb2 = *(const f32x2*)(lbp + h * 128 + 2 * kp);
.LBB0_1116:
	s_and_b32 s56, s68, 63
	s_lshl_b32 s57, s56, 6
	s_bfe_u32 s91, s68, 0x40006
	s_or_b32 s33, s90, s57
	s_and_b32 s75, s97, 3
	s_cmpk_lt_u32 s68, 0x400
	s_cselect_b32 s57, s95, s81
	s_cselect_b32 s68, s94, s80
	s_lshl_b32 s56, s56, 15
	s_lshl_b32 s90, s91, 21
	s_or_b32 s56, s90, s56
	s_add_u32 s56, s68, s56
	s_addc_u32 s57, s57, 0
	v_lshl_add_u64 v[20:21], s[56:57], 0, v[80:81]
	v_add_co_u32_e32 v12, vcc, s3, v20
	global_load_dwordx4 v[8:11], v80, s[56:57]
	s_nop 0
	v_addc_co_u32_e32 v13, vcc, 0, v21, vcc
	s_movk_i32 s56, 0x4000
	v_add_co_u32_e32 v16, vcc, s56, v20
	v_or_b32_e32 v42, s33, v101
	v_add_u32_e32 v44, s33, v102
	v_addc_co_u32_e32 v17, vcc, 0, v21, vcc
	s_movk_i32 s56, 0x6000
	s_lshl_b32 s68, s91, 8
	v_ashrrev_i32_e32 v43, 31, v42
	v_ashrrev_i32_e32 v45, 31, v44
	v_add_co_u32_e32 v20, vcc, s56, v20
	v_lshl_add_u64 v[40:41], v[84:85], 0, s[68:69]
	v_lshlrev_b64 v[96:97], 12, v[42:43]
	v_lshlrev_b64 v[94:95], 12, v[44:45]
	s_lshl_b32 s68, s91, 9
	v_addc_co_u32_e32 v21, vcc, 0, v21, vcc
	v_lshl_add_u64 v[42:43], v[40:41], 0, v[96:97]
	v_lshl_add_u64 v[40:41], v[40:41], 0, v[94:95]
	v_cvt_f32_f16_e32 v54, v48
	v_cvt_f32_f16_sdwa v55, v48 dst_sel:DWORD dst_unused:UNUSED_PAD src0_sel:WORD_1
	v_lshl_add_u64 v[48:49], v[86:87], 0, s[68:69]
	global_load_dwordx4 v[12:15], v[12:13], off
	s_nop 0
	global_load_dwordx4 v[16:19], v[16:17], off
	v_mul_f32_e32 v54, 0x3fb8aa3b, v54
	global_load_dwordx4 v[20:23], v[20:21], off
	s_nop 0
	global_load_dwordx4 v[44:47], v[42:43], off
	s_nop 0
	global_load_dwordx4 v[40:43], v[40:41], off
	v_exp_f32_e32 v54, v54
	global_load_dwordx2 v[58:59], v[48:49], off
	s_and_b64 vcc, exec, s[76:77]
	s_cbranch_vccnz .LBB0_1114
	s_lshl_b32 s56, s74, 2
	s_lshl_b32 s57, s74, 6
	s_and_b32 s56, s56, 0xfffff000
	s_and_b32 s57, s57, 0xfc0
	s_or_b32 s56, s56, s57
	v_readlane_b32 s57, v254, 3
	s_nop 0
	s_lshl_b32 s57, s57, 3
	s_add_i32 s56, s56, s57
	s_lshl_b32 s56, s56, 12
	s_lshl_b32 s57, s74, 1
	s_and_b32 s57, s57, 0x780
	s_lshl_b32 s57, s57, 1
	s_add_u32 s56, s56, s57
	s_add_u32 s98, s64, s56
	s_addc_u32 s99, s65, 0
	s_add_u32 s100, s66, s56
	s_addc_u32 s101, s67, 0
	v_lshlrev_b32_e32 v148, 1, v98
	global_load_dword v120, v148, s[98:99]
	global_load_dword v121, v148, s[100:101]
	s_add_u32 s98, s98, 0x1000
	s_addc_u32 s99, s99, 0
	s_add_u32 s100, s100, 0x1000
	s_addc_u32 s101, s101, 0
	global_load_dword v122, v148, s[98:99]
	global_load_dword v123, v148, s[100:101]
	s_add_u32 s98, s98, 0x1000
	s_addc_u32 s99, s99, 0
	s_add_u32 s100, s100, 0x1000
	s_addc_u32 s101, s101, 0
	global_load_dword v124, v148, s[98:99]
	global_load_dword v125, v148, s[100:101]
	s_add_u32 s98, s98, 0x1000
	s_addc_u32 s99, s99, 0
	s_add_u32 s100, s100, 0x1000
	s_addc_u32 s101, s101, 0
	global_load_dword v126, v148, s[98:99]
	global_load_dword v127, v148, s[100:101]
	s_add_u32 s98, s98, 0x1000
	s_addc_u32 s99, s99, 0
	s_add_u32 s100, s100, 0x1000
	s_addc_u32 s101, s101, 0
	global_load_dword v128, v148, s[98:99]
	global_load_dword v129, v148, s[100:101]
	s_add_u32 s98, s98, 0x1000
	s_addc_u32 s99, s99, 0
	s_add_u32 s100, s100, 0x1000
	s_addc_u32 s101, s101, 0
	global_load_dword v130, v148, s[98:99]
	global_load_dword v131, v148, s[100:101]
	s_add_u32 s98, s98, 0x1000
	s_addc_u32 s99, s99, 0
	s_add_u32 s100, s100, 0x1000
	s_addc_u32 s101, s101, 0
	global_load_dword v132, v148, s[98:99]
	global_load_dword v133, v148, s[100:101]
	s_add_u32 s98, s98, 0x1000
	s_addc_u32 s99, s99, 0
	s_add_u32 s100, s100, 0x1000
	s_addc_u32 s101, s101, 0
	global_load_dword v134, v148, s[98:99]
	global_load_dword v135, v148, s[100:101]
	s_mov_b32 s56, s74
	s_ashr_i32 s57, s74, 31
	s_lshl_b64 s[56:57], s[56:57], 14
	v_lshl_add_u64 v[148:149], v[82:83], 0, s[56:57]
	v_add_co_u32_e32 v150, vcc, 0x2000, v148
	s_nop 1
	v_addc_co_u32_e32 v151, vcc, 0, v149, vcc
	global_load_dwordx4 v[32:35], v[148:149], off
	global_load_dwordx4 v[36:39], v[150:151], off
